# scan + A pass 2 phase: waves 4-7 run A pass 2 first and the SSD scan second (waves 0-3 keep the order), so each SIMD pairs a memory-streaming wave with an attention wave
# speedup vs baseline: 1.0059x; 1.0059x over previous
; #define LAS __attribute__((address_space(3)))
; __global__ void __launch_bounds__(512) fwd_kernel(Args a) {
;     extern __shared__ __attribute__((aligned(16))) unsigned char lds_raw[];
;     cg::grid_group grid = cg::this_grid();
;     LAS unsigned char* lds = (LAS unsigned char*)lds_raw;
;     const int wave0 = __builtin_amdgcn_readfirstlane(threadIdx.x >> 6), G = gridDim.x;
;     ...
;     const int lo = a.ph_lo, hi = a.ph_hi;
;     if (hi > 1000) grid.sync();
_Z10fwd_kernel4Args:
	s_mov_b32 s100, 0
	s_load_dwordx8 s[76:83], s[0:1], 0x80
	s_load_dword s3, s[0:1], 0xa8
	s_load_dwordx2 s[88:89], s[0:1], 0xa0
	s_add_u32 s6, s0, 0xa0
	s_addc_u32 s7, s1, 0
	v_and_b32_e32 v1, 0x3ff, v0
	s_mov_b32 s66, s2
	s_movk_i32 s4, 0x3ff
	s_waitcnt lgkmcnt(0)
	s_cmpk_lt_i32 s83, 0x3e9
	v_readfirstlane_b32 s2, v1
	s_cbranch_scc1 .LBB0_12
	v_lshrrev_b32_e32 v2, 20, v0
	v_lshrrev_b32_e32 v0, 10, v0
	v_or_b32_e32 v0, v0, v2
	v_and_or_b32 v0, v0, s4, v1
	v_cmp_eq_u32_e32 vcc, 0, v0
	s_barrier
	s_and_saveexec_b64 s[4:5], vcc
	s_cbranch_execz .LBB0_11
	buffer_wbl2 sc1
	s_load_dwordx2 s[6:7], s[6:7], 0x58
	s_mov_b64 s[8:9], exec
	v_mbcnt_lo_u32_b32 v0, s8, 0
	v_mbcnt_hi_u32_b32 v0, s9, v0
	v_cmp_eq_u32_e32 vcc, 0, v0
	s_waitcnt lgkmcnt(0)
	s_load_dword s12, s[6:7], 0x28
	s_and_saveexec_b64 s[10:11], vcc
	s_cbranch_execz .LBB0_4
	s_bcnt1_i32_b64 s8, s[8:9]
	v_mov_b32_e32 v2, 0
	v_mov_b32_e32 v3, s8
	global_atomic_add v2, v2, v3, s[6:7] offset:32 sc0

; #define LAUNDER() int tp = TID0(); const int tid = tp, lane = tp & 63, wave = __builtin_amdgcn_readfirstlane(tp >> 6); (void)tid; (void)lane; (void)wave
; DI void ssd_scan(float* STATES, const float* TOT, int gtid, int gthreads) {
;     for (int it = gtid; it < 8 * 4 * 2 * 64 * 32; it += gthreads) {
;         const int n4 = it & 31, p = (it >> 5) & 63, dir = (it >> 11) & 1, h = (it >> 12) & 3, b = it >> 14;
;         f32x4 v[16]; float e[16];
; #pragma unroll
;         for (int st = 0; st < 16; ++st) { const int c = dir ? 15 - st : st; const int hd = ((b * 16 + c) * 4 + h) * 2 + dir;
;             v[st] = *(const f32x4*)(STATES + ((size_t)hd * 64 + p) * 128 + n4 * 4); e[st] = __expf(TOT[hd]); }
; __global__ void __launch_bounds__(512) fwd_kernel(Args a) {
;     ...
;         if (IN(pb + 3) && EN_SCAN) { LAUNDER(); ssd_scan(STATES, TOT, blockIdx.x * 512 + tid, G * 512); }
.Lsw_scan:
	s_cmp_eq_u32 s100, 0
	s_cbranch_scc0 .Lsw_doscan
	v_readlane_b32 s0, v253, 0
	s_nop 0
	s_cmp_lt_u32 s0, 0x100
	s_cbranch_scc1 .Lsw_doscan
	s_mov_b32 s100, 1
	s_branch .Lsw_a2
.Lsw_doscan:
	v_mbcnt_lo_u32_b32 v4, -1, 0
	v_mbcnt_hi_u32_b32 v4, -1, v4
	v_readlane_b32 s0, v254, 34
	s_nop 1
	v_add_u32_e32 v4, s0, v4
	s_mov_b32 s0, 0x20000
	v_cmp_gt_i32_e32 vcc, s0, v4
	s_and_saveexec_b64 s[0:1], vcc
	s_cbranch_execz .LBB0_419
	s_waitcnt lgkmcnt(0)
	v_lshlrev_b32_e32 v5, 2, v4
	s_mov_b64 s[20:21], 0

; #define LAS __attribute__((address_space(3)))
; DI float ex2(float x) { return __builtin_amdgcn_exp2f(x); }
; DI float a_bound(const bf16x8 (&qf)[2], const float* kmax_l, int b, int h) { return sqrtf(q_norm2(qf) * (kmax_l[b * 128 + 8 + 2 * h] + kmax_l[b * 128 + 9 + 2 * h])) * 1.01f + 0.05f; }
; #define LAUNDER() int tp = TID0(); const int tid = tp, lane = tp & 63, wave = __builtin_amdgcn_readfirstlane(tp >> 6); (void)tid; (void)lane; (void)wave
; DI void mixerA2_unit(int u, const bf16* PROJ, bf16* YC, const float* LPA, const float* kmax_l, LAS char* vt, int wave, int lane) {
;     const int b = u >> 6, h = (u >> 4) & 3, rho = u & 15, a0 = 16 * wave, r = lane & 15, g = lane >> 4;
;     const bf16* kb = slab(PROJ, C_AK + h * 64, b); const bf16* vb = slab(PROJ, C_AV + h * 64, b);
;     const int tq = 16 * (a0 + r) + rho;
;     bf16x8 qf[2];
; #pragma unroll
;     for (int ks = 0; ks < 2; ++ks) qf[ks] = *(const bf16x8*)(slab(PROJ, C_AQ + h * 64, b) + (size_t)tq * 64 + 32 * ks + 8 * g);
;     const float nslope2 = -ex2(-(float)(2 * h + 1)) * LOG2E;
;     const float bound = a_bound(qf, kmax_l, b, h);
;     const f32x4 cinit = {-bound, -bound, -bound, -bound};
;     f32x4 o[4], ol = {0.f, 0.f, 0.f, 0.f};
; #pragma unroll
;     for (int c = 0; c < 4; ++c) o[c] = ol;
; __global__ void __launch_bounds__(512) fwd_kernel(Args a) {
;     ...
;         if (IN(pb + 3) && EN_A) { LAUNDER(); LAS char* vt = (LAS char*)lds + wave * 16384;
;             for (int u = blockIdx.x; u < 512; u += G) { mixerA2_unit(u, PROJ, YC, LPA, KMAX + l * 1024, vt, wave, lane); } }
.LBB0_419:
	s_or_b64 exec, exec, s[0:1]
	s_cmp_eq_u32 s100, 2
	s_cbranch_scc0 .Lsw_a2
	s_mov_b32 s100, 0
	s_branch .LBB0_423
.Lsw_a2:
	v_readlane_b32 s0, v253, 0
	v_mbcnt_lo_u32_b32 v4, -1, 0
	v_mbcnt_hi_u32_b32 v4, -1, v4
	s_waitcnt lgkmcnt(0)
	s_nop 0
	v_add_u32_e32 v5, s0, v4
	v_readlane_b32 s0, v254, 31
	v_readlane_b32 s1, v254, 32
	s_andn2_b64 vcc, exec, s[0:1]
	v_readfirstlane_b32 s0, v5
	s_cbranch_vccnz .LBB0_423
	v_writelane_b32 v255, s26, 35
	s_ashr_i32 s2, s0, 6
	s_lshl_b32 s0, s2, 14
	v_writelane_b32 v255, s27, 36
	s_add_i32 s4, s0, 0
	v_readlane_b32 s0, v255, 27
	v_readlane_b32 s1, v255, 28
	s_lshl_b32 s34, s0, 10
	s_lshl_b64 s[0:1], s[34:35], 2
	v_readlane_b32 s20, v253, 42
	v_readlane_b32 s21, v253, 43
	s_add_u32 s60, s20, s0
	s_addc_u32 s61, s21, s1
	v_and_b32_e32 v7, 15, v4
	v_bfe_u32 v8, v4, 4, 2
	s_lshl_b32 s62, s2, 8
	v_lshl_or_b32 v149, v7, 4, s62
	v_lshlrev_b32_e32 v167, 6, v8
	v_lshlrev_b32_e32 v148, 3, v8
	v_sub_u32_e32 v8, v167, v149
	v_mov_b32_e32 v14, s4
	s_movk_i32 s0, 0x90
	v_mad_u32_u24 v169, v7, s0, v14
	v_add_u32_e32 v7, 0x400, v8
	v_cmp_gt_u32_e64 s[36:37], s14, v7
	v_add_u32_e32 v7, 16, v8
	v_cvt_f32_i32_e32 v171, v7
	v_add_u32_e32 v7, 32, v8
	v_and_b32_e32 v9, 64, v224
	v_add_u32_e32 v15, 0x410, v8
	v_cvt_f32_i32_e32 v172, v7
	v_add_u32_e32 v7, 48, v8
	s_add_i32 s63, s62, 0xffffff00
	s_add_i32 s64, s62, 0xffffff80
	v_xor_b32_e32 v6, 16, v224
	v_add_u32_e32 v9, 64, v9
	v_cmp_gt_u32_e64 s[38:39], s14, v15
	v_add_u32_e32 v15, 0x420, v8
	v_cvt_f32_i32_e32 v173, v7
	v_add_u32_e32 v7, 0x100, v8
	s_cmpk_lt_u32 s63, 0x800
	v_cmp_lt_i32_e32 vcc, v6, v9
	v_cmp_gt_u32_e64 s[40:41], s14, v15
	v_add_u32_e32 v15, 0x430, v8
	v_cvt_f32_i32_e32 v174, v7
	v_add_u32_e32 v7, 0x110, v8
	s_cselect_b64 s[54:55], -1, 0
	s_cmpk_lt_u32 s64, 0x800
	v_cndmask_b32_e32 v6, v224, v6, vcc
	v_cmp_gt_u32_e64 s[42:43], s14, v15
	v_add_u32_e32 v15, 0x500, v8
	v_cvt_f32_i32_e32 v175, v7
	v_add_u32_e32 v7, 0x120, v8
	s_cselect_b64 s[90:91], -1, 0
	s_add_i32 s65, s62, 0x100
	v_lshlrev_b32_e32 v160, 2, v6
	v_xor_b32_e32 v6, 32, v224
	v_cmp_gt_u32_e64 s[44:45], s14, v15
	v_add_u32_e32 v15, 0x510, v8
	v_cvt_f32_i32_e32 v176, v7
	v_add_u32_e32 v7, 0x130, v8
	s_cmpk_lt_u32 s62, 0x800
	v_and_b32_e32 v5, 63, v4
	v_cmp_lt_i32_e32 vcc, v6, v9
	v_bfe_u32 v9, v4, 3, 3
	v_lshlrev_b32_e32 v13, 4, v4
	v_cvt_f32_i32_e32 v170, v8
	v_cmp_gt_u32_e64 s[46:47], s14, v15
	v_add_u32_e32 v15, 0x520, v8
	v_add_u32_e32 v8, 0x530, v8
	v_cvt_f32_i32_e32 v177, v7
	s_cselect_b64 s[20:21], -1, 0
	s_add_i32 s68, s62, 0x180
	v_cndmask_b32_e32 v6, v224, v6, vcc
	v_lshlrev_b32_e32 v5, 3, v5
	v_or_b32_e32 v10, 8, v9
	v_and_b32_e32 v13, 0x70, v13
	v_cmp_gt_u32_e64 s[50:51], s14, v8
	v_bfe_u32 v7, v4, 2, 4
	s_cmpk_lt_u32 s65, 0x800
	v_and_b32_e32 v8, 7, v4
	v_lshlrev_b32_e32 v161, 2, v6
	v_and_b32_e32 v6, 56, v5
	v_or_b32_e32 v11, 16, v9
	v_or_b32_e32 v12, 24, v9
	v_add_u32_e32 v13, s4, v13
	v_mul_u32_u24_e32 v166, 0x90, v9
	v_and_b32_e32 v168, 48, v4
	v_mad_u32_u24 v7, v7, s0, v14
	v_and_b32_e32 v5, 24, v5
	s_mov_b64 s[56:57], s[96:97]
	s_cselect_b64 s[96:97], -1, 0
	s_cmpk_lt_u32 s68, 0x800
	v_lshlrev_b32_e32 v4, 3, v8
	v_lshl_add_u32 v182, v8, 4, s4
	v_mul_u32_u24_e32 v8, 0x90, v10
	v_lshlrev_b32_e32 v162, 4, v9
	v_lshlrev_b32_e32 v163, 4, v10
	v_lshlrev_b32_e32 v164, 4, v11
	v_lshlrev_b32_e32 v165, 4, v12
	v_cmp_gt_u32_e64 s[48:49], s14, v15
	v_lshlrev_b32_e32 v178, 2, v9
	v_lshlrev_b32_e32 v179, 2, v10
	v_lshlrev_b32_e32 v180, 2, v11
	v_lshlrev_b32_e32 v181, 2, v12
	s_cselect_b64 s[26:27], -1, 0
	v_lshlrev_b32_e32 v150, 1, v6
	v_add_u32_e32 v183, v13, v166
	v_add_u32_e32 v184, v7, v5
	v_lshlrev_b32_e32 v152, 1, v4
	v_add_u32_e32 v185, v182, v8
	s_mov_b32 s69, s66
	s_movk_i32 s58, 0x7bc
	s_movk_i32 s67, 0x7fc
	s_movk_i32 s59, 0x7b8
	s_movk_i32 s52, 0x7b4

; #define SEAM(k) do { if (lo <= (k) && (k) + 1 < hi) { XcdBarrier b2_ = bar; asm volatile("" : "+s"(b2_.bar)); xcd_barrier(b2_); } } while (0)
; __global__ void __launch_bounds__(512) fwd_kernel(Args a) {
;     ...
;             for (int u = blockIdx.x; u < 512; u += G) { mixerA2_unit(u, PROJ, YC, LPA, KMAX + l * 1024, vt, wave, lane); } }
;         SEAM(pb + 3);
.LBB0_423:
	s_cmp_eq_u32 s100, 1
	s_cbranch_scc0 .Lsw_cont
	s_mov_b32 s100, 2
	s_branch .Lsw_scan

; __global__ void __launch_bounds__(512) fwd_kernel(Args a) {
	.amdhsa_kernel _Z10fwd_kernel4Args
		.amdhsa_group_segment_fixed_size 0
		.amdhsa_private_segment_fixed_size 0
		.amdhsa_kernarg_size 416
		.amdhsa_user_sgpr_count 2
		.amdhsa_user_sgpr_dispatch_ptr 0
		.amdhsa_user_sgpr_queue_ptr 0
		.amdhsa_user_sgpr_kernarg_segment_ptr 1
		.amdhsa_user_sgpr_dispatch_id 0
		.amdhsa_user_sgpr_kernarg_preload_length 0
		.amdhsa_user_sgpr_kernarg_preload_offset 0
		.amdhsa_user_sgpr_private_segment_size 0
		.amdhsa_uses_dynamic_stack 0
		.amdhsa_enable_private_segment 0
		.amdhsa_system_sgpr_workgroup_id_x 1
		.amdhsa_system_sgpr_workgroup_id_y 0
		.amdhsa_system_sgpr_workgroup_id_z 0
		.amdhsa_system_sgpr_workgroup_info 0
		.amdhsa_system_vgpr_workitem_id 2
		.amdhsa_next_free_vgpr 256
		.amdhsa_next_free_sgpr 102
		.amdhsa_accum_offset 256
		.amdhsa_reserve_vcc 1
		.amdhsa_float_round_mode_32 0
		.amdhsa_float_round_mode_16_64 0
		.amdhsa_float_denorm_mode_32 3
		.amdhsa_float_denorm_mode_16_64 3
		.amdhsa_dx10_clamp 1
		.amdhsa_ieee_mode 1
		.amdhsa_fp16_overflow 0
		.amdhsa_tg_split 0
		.amdhsa_exception_fp_ieee_invalid_op 0
		.amdhsa_exception_fp_denorm_src 0
		.amdhsa_exception_fp_ieee_div_zero 0
		.amdhsa_exception_fp_ieee_overflow 0
		.amdhsa_exception_fp_ieee_underflow 0
		.amdhsa_exception_fp_ieee_inexact 0
		.amdhsa_exception_int_div_zero 0
	.end_amdhsa_kernel

; __global__ void __launch_bounds__(512) fwd_kernel(Args a) {
amdhsa.kernels:
  - .agpr_count:     0
    .args:
      - .offset:         0
        .size:           160
        .value_kind:     by_value
      - .offset:         160
        .size:           4
        .value_kind:     hidden_block_count_x
      - .offset:         164
        .size:           4
        .value_kind:     hidden_block_count_y
      - .offset:         168
        .size:           4
        .value_kind:     hidden_block_count_z
      - .offset:         172
        .size:           2
        .value_kind:     hidden_group_size_x
      - .offset:         174
        .size:           2
        .value_kind:     hidden_group_size_y
      - .offset:         176
        .size:           2
        .value_kind:     hidden_group_size_z
      - .offset:         178
        .size:           2
        .value_kind:     hidden_remainder_x
      - .offset:         180
        .size:           2
        .value_kind:     hidden_remainder_y
      - .offset:         182
        .size:           2
        .value_kind:     hidden_remainder_z
      - .offset:         200
        .size:           8
        .value_kind:     hidden_global_offset_x
      - .offset:         208
        .size:           8
        .value_kind:     hidden_global_offset_y
      - .offset:         216
        .size:           8
        .value_kind:     hidden_global_offset_z
      - .offset:         224
        .size:           2
        .value_kind:     hidden_grid_dims
      - .offset:         248
        .size:           8
        .value_kind:     hidden_multigrid_sync_arg
      - .offset:         280
        .size:           4
        .value_kind:     hidden_dynamic_lds_size
    .group_segment_fixed_size: 0
    .kernarg_segment_align: 8
    .kernarg_segment_size: 416
    .language:       OpenCL C
    .language_version:
      - 2
      - 0
    .max_flat_workgroup_size: 512
    .name:           _Z10fwd_kernel4Args
    .private_segment_fixed_size: 0
    .sgpr_count:     108
    .sgpr_spill_count: 165
    .symbol:         _Z10fwd_kernel4Args.kd
    .uniform_work_group_size: 1
    .uses_dynamic_stack: false
    .vgpr_count:     256
    .vgpr_spill_count: 0
    .wavefront_size: 64
